# first K-loop iteration peeled for the four zero-initialised GEMM loops: first MFMA per accumulator takes srcC=0, accumulator zeroing deleted
# speedup vs baseline: 1.0121x; 1.0023x over previous
.LBB0_292:
	s_add_u32 s19, s40, 0x100
	s_addc_u32 s54, s41, 0
	s_add_u32 s55, s38, 0x100
	v_mov_b32_e32 v2, 0
	s_addc_u32 s56, s39, 0
	s_mov_b32 s57, -2
	v_mov_b32_e32 v3, v2
	v_mov_b32_e32 v4, v2
	v_mov_b32_e32 v5, v2
	v_mov_b32_e32 v6, v2
	v_mov_b32_e32 v7, v2
	v_mov_b32_e32 v8, v2
	v_mov_b32_e32 v9, v2
	s_waitcnt vmcnt(0)
	s_cmp_eq_u32 s57, 28
	s_cselect_b32 s42, s10, s19
	s_cselect_b32 s43, s11, s54
	s_cselect_b32 s40, s26, s55
	s_cselect_b32 s41, s27, s56
	s_add_u32 s38, s42, 0x80
	s_addc_u32 s39, s43, 0
	s_add_i32 s60, 0, 0x10000
	s_add_i32 s61, 0, 0x14000
	v_add_u32_e32 v70, s60, v207
	v_add_u32_e32 v110, s61, v207
	ds_read_b128 v[42:45], v70
	ds_read_b128 v[46:49], v70 offset:1024
	ds_read_b128 v[66:69], v70 offset:2048
	ds_read_b128 v[70:73], v70 offset:3072
	ds_read_b128 v[86:89], v110
	ds_read_b128 v[90:93], v110 offset:1024
	ds_read_b128 v[106:109], v110 offset:2048
	ds_read_b128 v[110:113], v110 offset:3072
	s_add_u32 s58, s19, 0x7ff80
	s_addc_u32 s59, s54, 0
	ds_read_b128 v[130:133], v237
	ds_read_b128 v[134:137], v237 offset:1024
	ds_read_b128 v[154:157], v237 offset:2048
	ds_read_b128 v[158:161], v237 offset:3072
	ds_read_b128 v[178:181], v237 offset:4096
	ds_read_b128 v[182:185], v237 offset:5120
	ds_read_b128 v[186:189], v237 offset:6144
	ds_read_b128 v[190:193], v237 offset:7168
	s_add_i32 m0, s46, 0xc000
	v_lshl_add_u64 v[194:195], s[58:59], 0, v[208:209]
	s_add_u32 s58, s58, 0x40000
	s_addc_u32 s59, s59, 0
	global_load_lds_dwordx4 v[194:195], off
	s_add_i32 m0, s46, 0xe000
	v_lshl_add_u64 v[194:195], s[58:59], 0, v[208:209]
	global_load_lds_dwordx4 v[194:195], off
	s_waitcnt vmcnt(8)
	s_waitcnt lgkmcnt(0)
	s_barrier
	v_mfma_f32_16x16x32_bf16 v[174:177], v[42:45], v[130:133], 0
	v_mfma_f32_16x16x32_bf16 v[170:173], v[66:69], v[130:133], 0
	v_mfma_f32_16x16x32_bf16 v[150:153], v[42:45], v[154:157], 0
	v_mfma_f32_16x16x32_bf16 v[146:149], v[66:69], v[154:157], 0
	v_mfma_f32_16x16x32_bf16 v[126:129], v[42:45], v[178:181], 0
	v_mfma_f32_16x16x32_bf16 v[122:125], v[66:69], v[178:181], 0
	v_mfma_f32_16x16x32_bf16 v[102:105], v[42:45], v[186:189], 0
	v_mfma_f32_16x16x32_bf16 v[98:101], v[66:69], v[186:189], 0
	v_mfma_f32_16x16x32_bf16 v[174:177], v[46:49], v[134:137], v[174:177]
	v_mfma_f32_16x16x32_bf16 v[170:173], v[70:73], v[134:137], v[170:173]
	v_mfma_f32_16x16x32_bf16 v[150:153], v[46:49], v[158:161], v[150:153]
	v_mfma_f32_16x16x32_bf16 v[146:149], v[70:73], v[158:161], v[146:149]
	v_mfma_f32_16x16x32_bf16 v[126:129], v[46:49], v[182:185], v[126:129]
	v_mfma_f32_16x16x32_bf16 v[122:125], v[70:73], v[182:185], v[122:125]
	v_mfma_f32_16x16x32_bf16 v[102:105], v[46:49], v[190:193], v[102:105]
	v_mfma_f32_16x16x32_bf16 v[98:101], v[70:73], v[190:193], v[98:101]
	v_mfma_f32_16x16x32_bf16 v[166:169], v[86:89], v[130:133], 0
	v_mfma_f32_16x16x32_bf16 v[130:133], v[106:109], v[130:133], 0
	v_mfma_f32_16x16x32_bf16 v[138:141], v[106:109], v[154:157], 0
	v_mfma_f32_16x16x32_bf16 v[118:121], v[86:89], v[178:181], 0
	v_mfma_f32_16x16x32_bf16 v[114:117], v[106:109], v[178:181], 0
	v_mfma_f32_16x16x32_bf16 v[94:97], v[86:89], v[186:189], 0
	v_mfma_f32_16x16x32_bf16 v[82:85], v[106:109], v[186:189], 0
	v_mfma_f32_16x16x32_bf16 v[166:169], v[90:93], v[134:137], v[166:169]
	v_mfma_f32_16x16x32_bf16 v[130:133], v[110:113], v[134:137], v[130:133]
	v_mfma_f32_16x16x32_bf16 v[134:137], v[86:89], v[154:157], 0
	v_mfma_f32_16x16x32_bf16 v[138:141], v[110:113], v[158:161], v[138:141]
	v_mfma_f32_16x16x32_bf16 v[118:121], v[90:93], v[182:185], v[118:121]
	v_mfma_f32_16x16x32_bf16 v[114:117], v[110:113], v[182:185], v[114:117]
	v_mfma_f32_16x16x32_bf16 v[94:97], v[90:93], v[190:193], v[94:97]
	v_mfma_f32_16x16x32_bf16 v[82:85], v[110:113], v[190:193], v[82:85]
	v_mfma_f32_16x16x32_bf16 v[134:137], v[90:93], v[158:161], v[134:137]
	s_barrier
	s_mov_b64 s[58:59], s[40:41]
	ds_read_b128 v[142:145], v237 offset:16384
	ds_read_b128 v[154:157], v237 offset:17408
	ds_read_b128 v[158:161], v237 offset:18432
	ds_read_b128 v[162:165], v237 offset:19456
	ds_read_b128 v[178:181], v237 offset:20480
	ds_read_b128 v[182:185], v237 offset:21504
	ds_read_b128 v[186:189], v237 offset:22528
	ds_read_b128 v[190:193], v237 offset:23552
	s_add_i32 s60, s60, s45
	v_lshl_add_u64 v[194:195], s[58:59], 0, v[202:203]
	s_add_u32 s58, s58, 0x40000
	s_mov_b32 m0, s60
	s_addc_u32 s59, s59, 0
	global_load_lds_dwordx4 v[194:195], off
	s_add_i32 m0, s60, 0x2000
	v_lshl_add_u64 v[194:195], s[58:59], 0, v[202:203]
	s_add_u32 s58, s40, 0x80000
	s_addc_u32 s59, s41, 0
	global_load_lds_dwordx4 v[194:195], off
	s_add_i32 s60, s61, s45
	v_lshl_add_u64 v[194:195], s[58:59], 0, v[202:203]
	s_add_u32 s58, s58, 0x40000
	s_mov_b32 m0, s60
	s_addc_u32 s59, s59, 0
	global_load_lds_dwordx4 v[194:195], off
	s_add_i32 m0, s60, 0x2000
	v_lshl_add_u64 v[194:195], s[58:59], 0, v[202:203]
	s_mov_b64 s[58:59], s[42:43]
	global_load_lds_dwordx4 v[194:195], off
	s_mov_b32 m0, s46
	v_lshl_add_u64 v[194:195], s[58:59], 0, v[208:209]
	s_add_u32 s58, s58, 0x40000
	s_addc_u32 s59, s59, 0
	global_load_lds_dwordx4 v[194:195], off
	s_mov_b32 m0, s47
	v_lshl_add_u64 v[194:195], s[58:59], 0, v[208:209]
	global_load_lds_dwordx4 v[194:195], off
	s_waitcnt vmcnt(8)
	s_waitcnt lgkmcnt(0)
	s_barrier
	v_mfma_f32_16x16x32_bf16 v[78:81], v[42:45], v[142:145], 0
	v_mfma_f32_16x16x32_bf16 v[74:77], v[66:69], v[142:145], 0
	v_mfma_f32_16x16x32_bf16 v[54:57], v[42:45], v[158:161], 0
	v_mfma_f32_16x16x32_bf16 v[50:53], v[66:69], v[158:161], 0
	v_mfma_f32_16x16x32_bf16 v[30:33], v[42:45], v[178:181], 0
	v_mfma_f32_16x16x32_bf16 v[26:29], v[66:69], v[178:181], 0
	v_mfma_f32_16x16x32_bf16 v[14:17], v[42:45], v[186:189], 0
	v_mfma_f32_16x16x32_bf16 v[10:13], v[66:69], v[186:189], 0
	v_mfma_f32_16x16x32_bf16 v[78:81], v[46:49], v[154:157], v[78:81]
	v_mfma_f32_16x16x32_bf16 v[74:77], v[70:73], v[154:157], v[74:77]
	v_mfma_f32_16x16x32_bf16 v[54:57], v[46:49], v[162:165], v[54:57]
	v_mfma_f32_16x16x32_bf16 v[50:53], v[70:73], v[162:165], v[50:53]
	v_mfma_f32_16x16x32_bf16 v[30:33], v[46:49], v[182:185], v[30:33]
	v_mfma_f32_16x16x32_bf16 v[26:29], v[70:73], v[182:185], v[26:29]
	v_mfma_f32_16x16x32_bf16 v[14:17], v[46:49], v[190:193], v[14:17]
	v_mfma_f32_16x16x32_bf16 v[10:13], v[70:73], v[190:193], v[10:13]
	v_mfma_f32_16x16x32_bf16 v[38:41], v[86:89], v[158:161], 0
	v_mfma_f32_16x16x32_bf16 v[34:37], v[106:109], v[158:161], 0
	v_mfma_f32_16x16x32_bf16 v[22:25], v[86:89], v[178:181], 0
	v_mfma_f32_16x16x32_bf16 v[18:21], v[106:109], v[178:181], 0
	v_mfma_f32_16x16x32_bf16 v[6:9], v[86:89], v[186:189], v[6:9]
	v_mfma_f32_16x16x32_bf16 v[2:5], v[106:109], v[186:189], v[2:5]
	v_mfma_f32_16x16x32_bf16 v[42:45], v[86:89], v[142:145], 0
	v_mfma_f32_16x16x32_bf16 v[46:49], v[106:109], v[142:145], 0
	v_mfma_f32_16x16x32_bf16 v[38:41], v[90:93], v[162:165], v[38:41]
	v_mfma_f32_16x16x32_bf16 v[34:37], v[110:113], v[162:165], v[34:37]
	v_mfma_f32_16x16x32_bf16 v[22:25], v[90:93], v[182:185], v[22:25]
	v_mfma_f32_16x16x32_bf16 v[18:21], v[110:113], v[182:185], v[18:21]
	v_mfma_f32_16x16x32_bf16 v[6:9], v[90:93], v[190:193], v[6:9]
	v_mfma_f32_16x16x32_bf16 v[2:5], v[110:113], v[190:193], v[2:5]
	v_mfma_f32_16x16x32_bf16 v[42:45], v[90:93], v[154:157], v[42:45]
	v_mfma_f32_16x16x32_bf16 v[46:49], v[110:113], v[154:157], v[46:49]
	s_barrier
	s_add_i32 s58, 0, 0x18000
	s_add_i32 s59, 0, 0x1c000
	v_add_u32_e32 v70, s58, v207
	v_add_u32_e32 v110, s59, v207
	ds_read_b128 v[58:61], v70
	ds_read_b128 v[62:65], v70 offset:1024
	ds_read_b128 v[66:69], v70 offset:2048
	ds_read_b128 v[70:73], v70 offset:3072
	ds_read_b128 v[86:89], v110
	ds_read_b128 v[90:93], v110 offset:1024
	ds_read_b128 v[106:109], v110 offset:2048
	ds_read_b128 v[110:113], v110 offset:3072
	s_add_u32 s42, s42, 0x80000
	s_addc_u32 s43, s43, 0
	ds_read_b128 v[142:145], v237 offset:32768
	ds_read_b128 v[154:157], v237 offset:33792
	ds_read_b128 v[158:161], v237 offset:34816
	ds_read_b128 v[178:181], v237 offset:35840
	ds_read_b128 v[182:185], v237 offset:36864
	ds_read_b128 v[186:189], v237 offset:37888
	ds_read_b128 v[190:193], v237 offset:38912
	ds_read_b128 v[194:197], v237 offset:39936
	s_mov_b32 m0, s48
	v_lshl_add_u64 v[162:163], s[42:43], 0, v[208:209]
	s_add_u32 s42, s42, 0x40000
	s_addc_u32 s43, s43, 0
	global_load_lds_dwordx4 v[162:163], off
	s_mov_b32 m0, s49
	v_lshl_add_u64 v[162:163], s[42:43], 0, v[208:209]
	global_load_lds_dwordx4 v[162:163], off
	s_waitcnt vmcnt(8)
	s_waitcnt lgkmcnt(0)
	s_barrier
	v_mfma_f32_16x16x32_bf16 v[162:165], v[58:61], v[142:145], v[174:177]
	v_mfma_f32_16x16x32_bf16 v[174:177], v[62:65], v[154:157], v[162:165]
	v_mfma_f32_16x16x32_bf16 v[162:165], v[66:69], v[142:145], v[170:173]
	v_mfma_f32_16x16x32_bf16 v[150:153], v[58:61], v[158:161], v[150:153]
	v_mfma_f32_16x16x32_bf16 v[146:149], v[66:69], v[158:161], v[146:149]
	v_mfma_f32_16x16x32_bf16 v[126:129], v[58:61], v[182:185], v[126:129]
	v_mfma_f32_16x16x32_bf16 v[122:125], v[66:69], v[182:185], v[122:125]
	v_mfma_f32_16x16x32_bf16 v[102:105], v[58:61], v[190:193], v[102:105]
	v_mfma_f32_16x16x32_bf16 v[98:101], v[66:69], v[190:193], v[98:101]
	v_mfma_f32_16x16x32_bf16 v[170:173], v[70:73], v[154:157], v[162:165]
	v_mfma_f32_16x16x32_bf16 v[150:153], v[62:65], v[178:181], v[150:153]
	v_mfma_f32_16x16x32_bf16 v[146:149], v[70:73], v[178:181], v[146:149]
	v_mfma_f32_16x16x32_bf16 v[126:129], v[62:65], v[186:189], v[126:129]
	v_mfma_f32_16x16x32_bf16 v[122:125], v[70:73], v[186:189], v[122:125]
	v_mfma_f32_16x16x32_bf16 v[102:105], v[62:65], v[194:197], v[102:105]
	v_mfma_f32_16x16x32_bf16 v[98:101], v[70:73], v[194:197], v[98:101]
	v_mfma_f32_16x16x32_bf16 v[162:165], v[86:89], v[142:145], v[166:169]
	v_mfma_f32_16x16x32_bf16 v[130:133], v[106:109], v[142:145], v[130:133]
	v_mfma_f32_16x16x32_bf16 v[166:169], v[90:93], v[154:157], v[162:165]
	v_mfma_f32_16x16x32_bf16 v[162:165], v[110:113], v[154:157], v[130:133]
	v_mfma_f32_16x16x32_bf16 v[130:133], v[86:89], v[158:161], v[134:137]
	v_mfma_f32_16x16x32_bf16 v[142:145], v[90:93], v[178:181], v[130:133]
	v_mfma_f32_16x16x32_bf16 v[130:133], v[106:109], v[158:161], v[138:141]
	v_mfma_f32_16x16x32_bf16 v[118:121], v[86:89], v[182:185], v[118:121]
	v_mfma_f32_16x16x32_bf16 v[114:117], v[106:109], v[182:185], v[114:117]
	v_mfma_f32_16x16x32_bf16 v[94:97], v[86:89], v[190:193], v[94:97]
	v_mfma_f32_16x16x32_bf16 v[82:85], v[106:109], v[190:193], v[82:85]
	v_mfma_f32_16x16x32_bf16 v[138:141], v[110:113], v[178:181], v[130:133]
	v_mfma_f32_16x16x32_bf16 v[118:121], v[90:93], v[186:189], v[118:121]
	v_mfma_f32_16x16x32_bf16 v[114:117], v[110:113], v[186:189], v[114:117]
	v_mfma_f32_16x16x32_bf16 v[94:97], v[90:93], v[194:197], v[94:97]
	v_mfma_f32_16x16x32_bf16 v[82:85], v[110:113], v[194:197], v[82:85]
	s_barrier
	s_add_u32 s42, s40, 0x80
	s_addc_u32 s43, s41, 0
	ds_read_b128 v[130:133], v237 offset:49152
	ds_read_b128 v[134:137], v237 offset:50176
	ds_read_b128 v[154:157], v237 offset:51200
	ds_read_b128 v[158:161], v237 offset:52224
	ds_read_b128 v[178:181], v237 offset:53248
	ds_read_b128 v[182:185], v237 offset:54272
	ds_read_b128 v[186:189], v237 offset:55296
	ds_read_b128 v[190:193], v237 offset:56320
	s_add_i32 s58, s58, s45
	v_lshl_add_u64 v[194:195], s[42:43], 0, v[202:203]
	s_mov_b32 m0, s58
	s_add_u32 s42, s42, 0x40000
	global_load_lds_dwordx4 v[194:195], off
	s_addc_u32 s43, s43, 0
	s_add_i32 m0, s58, 0x2000
	s_add_u32 s40, s40, 0x80080
	s_addc_u32 s41, s41, 0
	v_lshl_add_u64 v[194:195], s[42:43], 0, v[202:203]
	global_load_lds_dwordx4 v[194:195], off
	s_add_i32 s42, s59, s45
	v_lshl_add_u64 v[194:195], s[40:41], 0, v[202:203]
	s_add_u32 s40, s40, 0x40000
	s_mov_b32 m0, s42
	s_addc_u32 s41, s41, 0
	global_load_lds_dwordx4 v[194:195], off
	s_add_i32 m0, s42, 0x2000
	v_lshl_add_u64 v[194:195], s[40:41], 0, v[202:203]
	global_load_lds_dwordx4 v[194:195], off
	s_mov_b32 m0, s50
	v_lshl_add_u64 v[194:195], s[38:39], 0, v[208:209]
	s_add_u32 s38, s38, 0x40000
	s_addc_u32 s39, s39, 0
	global_load_lds_dwordx4 v[194:195], off
	s_mov_b32 m0, s51
	v_lshl_add_u64 v[194:195], s[38:39], 0, v[208:209]
	global_load_lds_dwordx4 v[194:195], off
	s_waitcnt vmcnt(8)
	s_waitcnt lgkmcnt(0)
	s_barrier
	v_mfma_f32_16x16x32_bf16 v[78:81], v[58:61], v[130:133], v[78:81]
	v_mfma_f32_16x16x32_bf16 v[74:77], v[66:69], v[130:133], v[74:77]
	v_mfma_f32_16x16x32_bf16 v[54:57], v[58:61], v[154:157], v[54:57]
	v_mfma_f32_16x16x32_bf16 v[50:53], v[66:69], v[154:157], v[50:53]
	v_mfma_f32_16x16x32_bf16 v[30:33], v[58:61], v[178:181], v[30:33]
	v_mfma_f32_16x16x32_bf16 v[26:29], v[66:69], v[178:181], v[26:29]
	v_mfma_f32_16x16x32_bf16 v[14:17], v[58:61], v[186:189], v[14:17]
	v_mfma_f32_16x16x32_bf16 v[10:13], v[66:69], v[186:189], v[10:13]
	v_mfma_f32_16x16x32_bf16 v[78:81], v[62:65], v[134:137], v[78:81]
	v_mfma_f32_16x16x32_bf16 v[74:77], v[70:73], v[134:137], v[74:77]
	v_mfma_f32_16x16x32_bf16 v[54:57], v[62:65], v[158:161], v[54:57]
	v_mfma_f32_16x16x32_bf16 v[50:53], v[70:73], v[158:161], v[50:53]
	v_mfma_f32_16x16x32_bf16 v[30:33], v[62:65], v[182:185], v[30:33]
	v_mfma_f32_16x16x32_bf16 v[26:29], v[70:73], v[182:185], v[26:29]
	v_mfma_f32_16x16x32_bf16 v[14:17], v[62:65], v[190:193], v[14:17]
	v_mfma_f32_16x16x32_bf16 v[10:13], v[70:73], v[190:193], v[10:13]
	v_mfma_f32_16x16x32_bf16 v[42:45], v[86:89], v[130:133], v[42:45]
	v_mfma_f32_16x16x32_bf16 v[62:65], v[90:93], v[134:137], v[42:45]
	v_mfma_f32_16x16x32_bf16 v[42:45], v[106:109], v[130:133], v[46:49]
	v_mfma_f32_16x16x32_bf16 v[38:41], v[86:89], v[154:157], v[38:41]
	v_mfma_f32_16x16x32_bf16 v[34:37], v[106:109], v[154:157], v[34:37]
	v_mfma_f32_16x16x32_bf16 v[22:25], v[86:89], v[178:181], v[22:25]
	v_mfma_f32_16x16x32_bf16 v[18:21], v[106:109], v[178:181], v[18:21]
	v_mfma_f32_16x16x32_bf16 v[6:9], v[86:89], v[186:189], v[6:9]
	v_mfma_f32_16x16x32_bf16 v[2:5], v[106:109], v[186:189], v[2:5]
	v_mfma_f32_16x16x32_bf16 v[58:61], v[110:113], v[134:137], v[42:45]
	v_mfma_f32_16x16x32_bf16 v[38:41], v[90:93], v[158:161], v[38:41]
	v_mfma_f32_16x16x32_bf16 v[34:37], v[110:113], v[158:161], v[34:37]
	v_mfma_f32_16x16x32_bf16 v[22:25], v[90:93], v[182:185], v[22:25]
	v_mfma_f32_16x16x32_bf16 v[18:21], v[110:113], v[182:185], v[18:21]
	v_mfma_f32_16x16x32_bf16 v[6:9], v[90:93], v[190:193], v[6:9]
	v_mfma_f32_16x16x32_bf16 v[2:5], v[110:113], v[190:193], v[2:5]
	s_barrier
	s_add_i32 s57, s57, 2
	s_add_u32 s19, s19, 0x100
	s_addc_u32 s54, s54, 0
	s_add_u32 s55, s55, 0x100
	s_addc_u32 s56, s56, 0
	s_cmp_gt_u32 s57, 29
	s_cbranch_scc1 .Lpeel0_exit

.Lpeel0_exit:
	s_and_b64 vcc, exec, s[16:17]
	s_cbranch_vccz .LBB0_296
	s_barrier

.LBB0_1012:
	s_add_u32 s28, s44, 0x100
	s_addc_u32 s29, s45, 0
	s_add_u32 s76, s10, 0x100
	v_mov_b32_e32 v2, 0
	s_addc_u32 s77, s11, 0
	s_mov_b32 s10, 0
	v_mov_b32_e32 v3, v2
	v_mov_b32_e32 v4, v2
	v_mov_b32_e32 v5, v2
	v_mov_b32_e32 v6, v2
	v_mov_b32_e32 v7, v2
	v_mov_b32_e32 v8, v2
	v_mov_b32_e32 v9, v2
	v_mov_b32_e32 v14, v2
	v_mov_b32_e32 v15, v2
	v_mov_b32_e32 v16, v2
	v_mov_b32_e32 v17, v2
	s_waitcnt vmcnt(0)
	s_add_i32 s78, s10, 2
	s_cmp_eq_u32 s71, s10
	s_cselect_b32 s46, s4, s28
	s_cselect_b32 s47, s5, s29
	s_cselect_b32 s44, s42, s76
	s_cselect_b32 s45, s43, s77
	s_add_u32 s10, s46, 0x80
	s_addc_u32 s11, s47, 0
	s_add_i32 s79, 0, 0x10000
	s_add_i32 s82, 0, 0x14000
	v_add_u32_e32 v142, s79, v179
	v_add_u32_e32 v160, s82, v179
	ds_read_b128 v[130:133], v142
	ds_read_b128 v[134:137], v142 offset:1024
	ds_read_b128 v[138:141], v142 offset:2048
	ds_read_b128 v[142:145], v142 offset:3072
	ds_read_b128 v[146:149], v160
	ds_read_b128 v[150:153], v160 offset:1024
	ds_read_b128 v[154:157], v160 offset:2048
	ds_read_b128 v[160:163], v160 offset:3072
	s_add_u32 s80, s28, 0x7ff80
	v_add_u32_e32 v240, 0, v178
	s_addc_u32 s81, s29, 0
	ds_read_b128 v[164:167], v240
	ds_read_b128 v[168:171], v240 offset:1024
	ds_read_b128 v[172:175], v240 offset:2048
	ds_read_b128 v[212:215], v240 offset:3072
	ds_read_b128 v[216:219], v240 offset:4096
	ds_read_b128 v[220:223], v240 offset:5120
	ds_read_b128 v[224:227], v240 offset:6144
	ds_read_b128 v[236:239], v240 offset:7168
	s_add_i32 m0, s49, 0xc000
	v_lshl_add_u64 v[176:177], s[80:81], 0, v[158:159]
	s_add_u32 s80, s80, 0x40000
	s_addc_u32 s81, s81, 0
	global_load_lds_dwordx4 v[176:177], off
	s_add_i32 m0, s49, 0xe000
	v_lshl_add_u64 v[176:177], s[80:81], 0, v[158:159]
	global_load_lds_dwordx4 v[176:177], off
	s_waitcnt vmcnt(8)
	s_waitcnt lgkmcnt(0)
	s_barrier
	v_mfma_f32_16x16x32_bf16 v[126:129], v[130:133], v[164:167], 0
	v_mfma_f32_16x16x32_bf16 v[122:125], v[138:141], v[164:167], 0
	v_mfma_f32_16x16x32_bf16 v[114:117], v[130:133], v[172:175], 0
	v_mfma_f32_16x16x32_bf16 v[106:109], v[138:141], v[172:175], 0
	v_mfma_f32_16x16x32_bf16 v[98:101], v[130:133], v[216:219], 0
	v_mfma_f32_16x16x32_bf16 v[90:93], v[138:141], v[216:219], 0
	v_mfma_f32_16x16x32_bf16 v[82:85], v[130:133], v[224:227], 0
	v_mfma_f32_16x16x32_bf16 v[74:77], v[138:141], v[224:227], 0
	v_mfma_f32_16x16x32_bf16 v[126:129], v[134:137], v[168:171], v[126:129]
	v_mfma_f32_16x16x32_bf16 v[122:125], v[142:145], v[168:171], v[122:125]
	v_mfma_f32_16x16x32_bf16 v[114:117], v[134:137], v[212:215], v[114:117]
	v_mfma_f32_16x16x32_bf16 v[106:109], v[142:145], v[212:215], v[106:109]
	v_mfma_f32_16x16x32_bf16 v[98:101], v[134:137], v[220:223], v[98:101]
	v_mfma_f32_16x16x32_bf16 v[90:93], v[142:145], v[220:223], v[90:93]
	v_mfma_f32_16x16x32_bf16 v[82:85], v[134:137], v[236:239], v[82:85]
	v_mfma_f32_16x16x32_bf16 v[74:77], v[142:145], v[236:239], v[74:77]
	v_mfma_f32_16x16x32_bf16 v[118:121], v[146:149], v[164:167], 0
	v_mfma_f32_16x16x32_bf16 v[110:113], v[154:157], v[164:167], 0
	v_mfma_f32_16x16x32_bf16 v[102:105], v[146:149], v[172:175], 0
	v_mfma_f32_16x16x32_bf16 v[94:97], v[154:157], v[172:175], 0
	v_mfma_f32_16x16x32_bf16 v[86:89], v[146:149], v[216:219], 0
	v_mfma_f32_16x16x32_bf16 v[78:81], v[154:157], v[216:219], 0
	v_mfma_f32_16x16x32_bf16 v[70:73], v[146:149], v[224:227], 0
	v_mfma_f32_16x16x32_bf16 v[66:69], v[154:157], v[224:227], 0
	v_mfma_f32_16x16x32_bf16 v[118:121], v[150:153], v[168:171], v[118:121]
	v_mfma_f32_16x16x32_bf16 v[110:113], v[160:163], v[168:171], v[110:113]
	v_mfma_f32_16x16x32_bf16 v[102:105], v[150:153], v[212:215], v[102:105]
	v_mfma_f32_16x16x32_bf16 v[94:97], v[160:163], v[212:215], v[94:97]
	v_mfma_f32_16x16x32_bf16 v[86:89], v[150:153], v[220:223], v[86:89]
	v_mfma_f32_16x16x32_bf16 v[78:81], v[160:163], v[220:223], v[78:81]
	v_mfma_f32_16x16x32_bf16 v[70:73], v[150:153], v[236:239], v[70:73]
	v_mfma_f32_16x16x32_bf16 v[66:69], v[160:163], v[236:239], v[66:69]
	s_barrier
	s_mov_b64 s[80:81], s[44:45]
	ds_read_b128 v[164:167], v240 offset:16384
	ds_read_b128 v[168:171], v240 offset:17408
	ds_read_b128 v[172:175], v240 offset:18432
	ds_read_b128 v[212:215], v240 offset:19456
	ds_read_b128 v[216:219], v240 offset:20480
	ds_read_b128 v[220:223], v240 offset:21504
	ds_read_b128 v[224:227], v240 offset:22528
	ds_read_b128 v[236:239], v240 offset:23552
	s_add_i32 s79, s79, s48
	v_lshl_add_u64 v[176:177], s[80:81], 0, v[202:203]
	s_add_u32 s80, s80, 0x30000
	s_mov_b32 m0, s79
	s_addc_u32 s81, s81, 0
	global_load_lds_dwordx4 v[176:177], off
	s_add_i32 m0, s79, 0x2000
	v_lshl_add_u64 v[176:177], s[80:81], 0, v[202:203]
	s_add_u32 s80, s44, 0x60000
	s_addc_u32 s81, s45, 0
	global_load_lds_dwordx4 v[176:177], off
	s_add_i32 s79, s82, s48
	v_lshl_add_u64 v[176:177], s[80:81], 0, v[202:203]
	s_add_u32 s80, s80, 0x30000
	s_mov_b32 m0, s79
	s_addc_u32 s81, s81, 0
	global_load_lds_dwordx4 v[176:177], off
	s_add_i32 m0, s79, 0x2000
	v_lshl_add_u64 v[176:177], s[80:81], 0, v[202:203]
	s_mov_b64 s[80:81], s[46:47]
	global_load_lds_dwordx4 v[176:177], off
	s_mov_b32 m0, s49
	v_lshl_add_u64 v[176:177], s[80:81], 0, v[158:159]
	s_add_u32 s80, s80, 0x40000
	s_addc_u32 s81, s81, 0
	global_load_lds_dwordx4 v[176:177], off
	s_mov_b32 m0, s50
	v_lshl_add_u64 v[176:177], s[80:81], 0, v[158:159]
	global_load_lds_dwordx4 v[176:177], off
	s_waitcnt vmcnt(8)
	s_waitcnt lgkmcnt(0)
	s_barrier
	v_mfma_f32_16x16x32_bf16 v[62:65], v[130:133], v[164:167], 0
	v_mfma_f32_16x16x32_bf16 v[58:61], v[138:141], v[164:167], 0
	v_mfma_f32_16x16x32_bf16 v[50:53], v[130:133], v[172:175], 0
	v_mfma_f32_16x16x32_bf16 v[42:45], v[138:141], v[172:175], 0
	v_mfma_f32_16x16x32_bf16 v[34:37], v[130:133], v[216:219], 0
	v_mfma_f32_16x16x32_bf16 v[26:29], v[138:141], v[216:219], 0
	v_mfma_f32_16x16x32_bf16 v[18:21], v[130:133], v[224:227], 0
	v_mfma_f32_16x16x32_bf16 v[10:13], v[138:141], v[224:227], 0
	v_mfma_f32_16x16x32_bf16 v[62:65], v[134:137], v[168:171], v[62:65]
	v_mfma_f32_16x16x32_bf16 v[58:61], v[142:145], v[168:171], v[58:61]
	v_mfma_f32_16x16x32_bf16 v[50:53], v[134:137], v[212:215], v[50:53]
	v_mfma_f32_16x16x32_bf16 v[42:45], v[142:145], v[212:215], v[42:45]
	v_mfma_f32_16x16x32_bf16 v[34:37], v[134:137], v[220:223], v[34:37]
	v_mfma_f32_16x16x32_bf16 v[26:29], v[142:145], v[220:223], v[26:29]
	v_mfma_f32_16x16x32_bf16 v[18:21], v[134:137], v[236:239], v[18:21]
	v_mfma_f32_16x16x32_bf16 v[10:13], v[142:145], v[236:239], v[10:13]
	v_mfma_f32_16x16x32_bf16 v[54:57], v[146:149], v[164:167], 0
	v_mfma_f32_16x16x32_bf16 v[46:49], v[154:157], v[164:167], 0
	v_mfma_f32_16x16x32_bf16 v[38:41], v[146:149], v[172:175], 0
	v_mfma_f32_16x16x32_bf16 v[30:33], v[154:157], v[172:175], 0
	v_mfma_f32_16x16x32_bf16 v[22:25], v[146:149], v[216:219], 0
	v_mfma_f32_16x16x32_bf16 v[14:17], v[154:157], v[216:219], v[14:17]
	v_mfma_f32_16x16x32_bf16 v[6:9], v[146:149], v[224:227], v[6:9]
	v_mfma_f32_16x16x32_bf16 v[2:5], v[154:157], v[224:227], v[2:5]
	v_mfma_f32_16x16x32_bf16 v[54:57], v[150:153], v[168:171], v[54:57]
	v_mfma_f32_16x16x32_bf16 v[46:49], v[160:163], v[168:171], v[46:49]
	v_mfma_f32_16x16x32_bf16 v[38:41], v[150:153], v[212:215], v[38:41]
	v_mfma_f32_16x16x32_bf16 v[30:33], v[160:163], v[212:215], v[30:33]
	v_mfma_f32_16x16x32_bf16 v[22:25], v[150:153], v[220:223], v[22:25]
	v_mfma_f32_16x16x32_bf16 v[14:17], v[160:163], v[220:223], v[14:17]
	v_mfma_f32_16x16x32_bf16 v[6:9], v[150:153], v[236:239], v[6:9]
	v_mfma_f32_16x16x32_bf16 v[2:5], v[160:163], v[236:239], v[2:5]
	s_barrier
	s_add_i32 s79, 0, 0x18000
	s_add_i32 s80, 0, 0x1c000
	v_add_u32_e32 v142, s79, v179
	v_add_u32_e32 v160, s80, v179
	ds_read_b128 v[130:133], v142
	ds_read_b128 v[134:137], v142 offset:1024
	ds_read_b128 v[138:141], v142 offset:2048
	ds_read_b128 v[142:145], v142 offset:3072
	ds_read_b128 v[146:149], v160
	ds_read_b128 v[150:153], v160 offset:1024
	ds_read_b128 v[154:157], v160 offset:2048
	ds_read_b128 v[160:163], v160 offset:3072
	s_add_u32 s46, s46, 0x80000
	s_addc_u32 s47, s47, 0
	ds_read_b128 v[164:167], v240 offset:32768
	ds_read_b128 v[168:171], v240 offset:33792
	ds_read_b128 v[172:175], v240 offset:34816
	ds_read_b128 v[212:215], v240 offset:35840
	ds_read_b128 v[216:219], v240 offset:36864
	ds_read_b128 v[220:223], v240 offset:37888
	ds_read_b128 v[224:227], v240 offset:38912
	ds_read_b128 v[236:239], v240 offset:39936
	s_mov_b32 m0, s51
	v_lshl_add_u64 v[176:177], s[46:47], 0, v[158:159]
	s_add_u32 s46, s46, 0x40000
	s_addc_u32 s47, s47, 0
	global_load_lds_dwordx4 v[176:177], off
	s_mov_b32 m0, s52
	v_lshl_add_u64 v[176:177], s[46:47], 0, v[158:159]
	global_load_lds_dwordx4 v[176:177], off
	s_waitcnt vmcnt(8)
	s_waitcnt lgkmcnt(0)
	s_barrier
	v_mfma_f32_16x16x32_bf16 v[126:129], v[130:133], v[164:167], v[126:129]
	v_mfma_f32_16x16x32_bf16 v[122:125], v[138:141], v[164:167], v[122:125]
	v_mfma_f32_16x16x32_bf16 v[114:117], v[130:133], v[172:175], v[114:117]
	v_mfma_f32_16x16x32_bf16 v[106:109], v[138:141], v[172:175], v[106:109]
	v_mfma_f32_16x16x32_bf16 v[98:101], v[130:133], v[216:219], v[98:101]
	v_mfma_f32_16x16x32_bf16 v[90:93], v[138:141], v[216:219], v[90:93]
	v_mfma_f32_16x16x32_bf16 v[82:85], v[130:133], v[224:227], v[82:85]
	v_mfma_f32_16x16x32_bf16 v[74:77], v[138:141], v[224:227], v[74:77]
	v_mfma_f32_16x16x32_bf16 v[126:129], v[134:137], v[168:171], v[126:129]
	v_mfma_f32_16x16x32_bf16 v[122:125], v[142:145], v[168:171], v[122:125]
	v_mfma_f32_16x16x32_bf16 v[114:117], v[134:137], v[212:215], v[114:117]
	v_mfma_f32_16x16x32_bf16 v[106:109], v[142:145], v[212:215], v[106:109]
	v_mfma_f32_16x16x32_bf16 v[98:101], v[134:137], v[220:223], v[98:101]
	v_mfma_f32_16x16x32_bf16 v[90:93], v[142:145], v[220:223], v[90:93]
	v_mfma_f32_16x16x32_bf16 v[82:85], v[134:137], v[236:239], v[82:85]
	v_mfma_f32_16x16x32_bf16 v[74:77], v[142:145], v[236:239], v[74:77]
	v_mfma_f32_16x16x32_bf16 v[118:121], v[146:149], v[164:167], v[118:121]
	v_mfma_f32_16x16x32_bf16 v[110:113], v[154:157], v[164:167], v[110:113]
	v_mfma_f32_16x16x32_bf16 v[102:105], v[146:149], v[172:175], v[102:105]
	v_mfma_f32_16x16x32_bf16 v[94:97], v[154:157], v[172:175], v[94:97]
	v_mfma_f32_16x16x32_bf16 v[86:89], v[146:149], v[216:219], v[86:89]
	v_mfma_f32_16x16x32_bf16 v[78:81], v[154:157], v[216:219], v[78:81]
	v_mfma_f32_16x16x32_bf16 v[70:73], v[146:149], v[224:227], v[70:73]
	v_mfma_f32_16x16x32_bf16 v[66:69], v[154:157], v[224:227], v[66:69]
	v_mfma_f32_16x16x32_bf16 v[118:121], v[150:153], v[168:171], v[118:121]
	v_mfma_f32_16x16x32_bf16 v[110:113], v[160:163], v[168:171], v[110:113]
	v_mfma_f32_16x16x32_bf16 v[102:105], v[150:153], v[212:215], v[102:105]
	v_mfma_f32_16x16x32_bf16 v[94:97], v[160:163], v[212:215], v[94:97]
	v_mfma_f32_16x16x32_bf16 v[86:89], v[150:153], v[220:223], v[86:89]
	v_mfma_f32_16x16x32_bf16 v[78:81], v[160:163], v[220:223], v[78:81]
	v_mfma_f32_16x16x32_bf16 v[70:73], v[150:153], v[236:239], v[70:73]
	v_mfma_f32_16x16x32_bf16 v[66:69], v[160:163], v[236:239], v[66:69]
	s_barrier
	s_add_u32 s46, s44, 0x80
	s_addc_u32 s47, s45, 0
	ds_read_b128 v[164:167], v240 offset:49152
	ds_read_b128 v[168:171], v240 offset:50176
	ds_read_b128 v[172:175], v240 offset:51200
	ds_read_b128 v[212:215], v240 offset:52224
	ds_read_b128 v[216:219], v240 offset:53248
	ds_read_b128 v[220:223], v240 offset:54272
	ds_read_b128 v[224:227], v240 offset:55296
	ds_read_b128 v[236:239], v240 offset:56320
	s_add_i32 s79, s79, s48
	v_lshl_add_u64 v[176:177], s[46:47], 0, v[202:203]
	s_mov_b32 m0, s79
	s_add_u32 s46, s46, 0x30000
	global_load_lds_dwordx4 v[176:177], off
	s_addc_u32 s47, s47, 0
	s_add_i32 m0, s79, 0x2000
	s_add_u32 s44, s44, 0x60080
	s_addc_u32 s45, s45, 0
	v_lshl_add_u64 v[176:177], s[46:47], 0, v[202:203]
	global_load_lds_dwordx4 v[176:177], off
	s_add_i32 s46, s80, s48
	v_lshl_add_u64 v[176:177], s[44:45], 0, v[202:203]
	s_add_u32 s44, s44, 0x30000
	s_mov_b32 m0, s46
	s_addc_u32 s45, s45, 0
	global_load_lds_dwordx4 v[176:177], off
	s_add_i32 m0, s46, 0x2000
	v_lshl_add_u64 v[176:177], s[44:45], 0, v[202:203]
	global_load_lds_dwordx4 v[176:177], off
	s_mov_b32 m0, s53
	v_lshl_add_u64 v[176:177], s[10:11], 0, v[158:159]
	s_add_u32 s10, s10, 0x40000
	s_addc_u32 s11, s11, 0
	global_load_lds_dwordx4 v[176:177], off
	s_mov_b32 m0, s54
	v_lshl_add_u64 v[176:177], s[10:11], 0, v[158:159]
	global_load_lds_dwordx4 v[176:177], off
	s_waitcnt vmcnt(8)
	s_waitcnt lgkmcnt(0)
	s_barrier
	v_mfma_f32_16x16x32_bf16 v[62:65], v[130:133], v[164:167], v[62:65]
	v_mfma_f32_16x16x32_bf16 v[58:61], v[138:141], v[164:167], v[58:61]
	v_mfma_f32_16x16x32_bf16 v[50:53], v[130:133], v[172:175], v[50:53]
	v_mfma_f32_16x16x32_bf16 v[42:45], v[138:141], v[172:175], v[42:45]
	v_mfma_f32_16x16x32_bf16 v[34:37], v[130:133], v[216:219], v[34:37]
	v_mfma_f32_16x16x32_bf16 v[26:29], v[138:141], v[216:219], v[26:29]
	v_mfma_f32_16x16x32_bf16 v[18:21], v[130:133], v[224:227], v[18:21]
	v_mfma_f32_16x16x32_bf16 v[10:13], v[138:141], v[224:227], v[10:13]
	v_mfma_f32_16x16x32_bf16 v[62:65], v[134:137], v[168:171], v[62:65]
	v_mfma_f32_16x16x32_bf16 v[58:61], v[142:145], v[168:171], v[58:61]
	v_mfma_f32_16x16x32_bf16 v[50:53], v[134:137], v[212:215], v[50:53]
	v_mfma_f32_16x16x32_bf16 v[42:45], v[142:145], v[212:215], v[42:45]
	v_mfma_f32_16x16x32_bf16 v[34:37], v[134:137], v[220:223], v[34:37]
	v_mfma_f32_16x16x32_bf16 v[26:29], v[142:145], v[220:223], v[26:29]
	v_mfma_f32_16x16x32_bf16 v[18:21], v[134:137], v[236:239], v[18:21]
	v_mfma_f32_16x16x32_bf16 v[10:13], v[142:145], v[236:239], v[10:13]
	v_mfma_f32_16x16x32_bf16 v[54:57], v[146:149], v[164:167], v[54:57]
	v_mfma_f32_16x16x32_bf16 v[46:49], v[154:157], v[164:167], v[46:49]
	v_mfma_f32_16x16x32_bf16 v[38:41], v[146:149], v[172:175], v[38:41]
	v_mfma_f32_16x16x32_bf16 v[30:33], v[154:157], v[172:175], v[30:33]
	v_mfma_f32_16x16x32_bf16 v[22:25], v[146:149], v[216:219], v[22:25]
	v_mfma_f32_16x16x32_bf16 v[14:17], v[154:157], v[216:219], v[14:17]
	v_mfma_f32_16x16x32_bf16 v[6:9], v[146:149], v[224:227], v[6:9]
	v_mfma_f32_16x16x32_bf16 v[2:5], v[154:157], v[224:227], v[2:5]
	v_mfma_f32_16x16x32_bf16 v[54:57], v[150:153], v[168:171], v[54:57]
	v_mfma_f32_16x16x32_bf16 v[46:49], v[160:163], v[168:171], v[46:49]
	v_mfma_f32_16x16x32_bf16 v[38:41], v[150:153], v[212:215], v[38:41]
	v_mfma_f32_16x16x32_bf16 v[30:33], v[160:163], v[212:215], v[30:33]
	v_mfma_f32_16x16x32_bf16 v[22:25], v[150:153], v[220:223], v[22:25]
	v_mfma_f32_16x16x32_bf16 v[14:17], v[160:163], v[220:223], v[14:17]
	v_mfma_f32_16x16x32_bf16 v[6:9], v[150:153], v[236:239], v[6:9]
	v_mfma_f32_16x16x32_bf16 v[2:5], v[160:163], v[236:239], v[2:5]
	s_barrier
	s_add_u32 s28, s28, 0x100
	s_addc_u32 s29, s29, 0
	s_add_u32 s76, s76, 0x100
	s_addc_u32 s77, s77, 0
	s_cmp_ge_i32 s78, s69
	s_mov_b32 s10, s78
	s_cbranch_scc1 .Lpeel1_exit

.Lpeel1_exit:
	s_and_b64 vcc, exec, s[18:19]
	s_cbranch_vccz .LBB0_1016
	s_barrier

.LBB0_1025:
	s_mov_b32 s10, 0
	v_mov_b32_e32 v2, 0
	v_mov_b32_e32 v3, 0
	v_mov_b32_e32 v4, 0
	v_mov_b32_e32 v5, 0
	v_mov_b32_e32 v6, 0
	v_mov_b32_e32 v7, 0
	v_mov_b32_e32 v8, 0
	v_mov_b32_e32 v9, 0
	s_waitcnt vmcnt(0)
	s_add_i32 s28, s10, 2
	s_cmp_eq_u32 s71, s10
	s_cselect_b32 s46, s4, s74
	s_cselect_b32 s47, s5, s75
	s_cselect_b32 s44, s42, s72
	s_cselect_b32 s45, s43, s73
	s_add_u32 s10, s46, 0x80
	s_addc_u32 s11, s47, 0
	s_add_i32 s29, 0, 0x10000
	s_add_i32 s78, 0, 0x14000
	v_add_u32_e32 v142, s29, v179
	v_add_u32_e32 v160, s78, v179
	ds_read_b128 v[130:133], v142
	ds_read_b128 v[134:137], v142 offset:1024
	ds_read_b128 v[138:141], v142 offset:2048
	ds_read_b128 v[142:145], v142 offset:3072
	ds_read_b128 v[146:149], v160
	ds_read_b128 v[150:153], v160 offset:1024
	ds_read_b128 v[154:157], v160 offset:2048
	ds_read_b128 v[160:163], v160 offset:3072
	s_add_u32 s76, s74, 0x7ff80
	v_add_u32_e32 v200, 0, v178
	s_addc_u32 s77, s75, 0
	ds_read_b128 v[164:167], v200
	ds_read_b128 v[168:171], v200 offset:1024
	ds_read_b128 v[172:175], v200 offset:2048
	ds_read_b128 v[180:183], v200 offset:3072
	ds_read_b128 v[184:187], v200 offset:4096
	ds_read_b128 v[188:191], v200 offset:5120
	ds_read_b128 v[192:195], v200 offset:6144
	ds_read_b128 v[196:199], v200 offset:7168
	s_add_i32 m0, s49, 0xc000
	v_lshl_add_u64 v[176:177], s[76:77], 0, v[158:159]
	s_add_u32 s76, s76, 0x40000
	s_addc_u32 s77, s77, 0
	global_load_lds_dwordx4 v[176:177], off
	s_add_i32 m0, s49, 0xe000
	v_lshl_add_u64 v[176:177], s[76:77], 0, v[158:159]
	global_load_lds_dwordx4 v[176:177], off
	s_waitcnt vmcnt(8)
	s_waitcnt lgkmcnt(0)
	s_barrier
	v_mfma_i32_16x16x64_i8 v[126:129], v[130:133], v[164:167], 0
	v_mfma_i32_16x16x64_i8 v[122:125], v[138:141], v[164:167], 0
	v_mfma_i32_16x16x64_i8 v[118:121], v[130:133], v[172:175], 0
	v_mfma_i32_16x16x64_i8 v[114:117], v[138:141], v[172:175], 0
	v_mfma_i32_16x16x64_i8 v[102:105], v[130:133], v[184:187], 0
	v_mfma_i32_16x16x64_i8 v[98:101], v[138:141], v[184:187], 0
	v_mfma_i32_16x16x64_i8 v[86:89], v[130:133], v[192:195], 0
	v_mfma_i32_16x16x64_i8 v[82:85], v[138:141], v[192:195], 0
	v_mfma_i32_16x16x64_i8 v[126:129], v[134:137], v[168:171], v[126:129]
	v_mfma_i32_16x16x64_i8 v[122:125], v[142:145], v[168:171], v[122:125]
	v_mfma_i32_16x16x64_i8 v[118:121], v[134:137], v[180:183], v[118:121]
	v_mfma_i32_16x16x64_i8 v[114:117], v[142:145], v[180:183], v[114:117]
	v_mfma_i32_16x16x64_i8 v[102:105], v[134:137], v[188:191], v[102:105]
	v_mfma_i32_16x16x64_i8 v[98:101], v[142:145], v[188:191], v[98:101]
	v_mfma_i32_16x16x64_i8 v[86:89], v[134:137], v[196:199], v[86:89]
	v_mfma_i32_16x16x64_i8 v[82:85], v[142:145], v[196:199], v[82:85]
	v_mfma_i32_16x16x64_i8 v[110:113], v[146:149], v[164:167], 0
	v_mfma_i32_16x16x64_i8 v[106:109], v[154:157], v[164:167], 0
	v_mfma_i32_16x16x64_i8 v[94:97], v[146:149], v[172:175], 0
	v_mfma_i32_16x16x64_i8 v[90:93], v[154:157], v[172:175], 0
	v_mfma_i32_16x16x64_i8 v[78:81], v[146:149], v[184:187], 0
	v_mfma_i32_16x16x64_i8 v[74:77], v[154:157], v[184:187], 0
	v_mfma_i32_16x16x64_i8 v[70:73], v[146:149], v[192:195], 0
	v_mfma_i32_16x16x64_i8 v[66:69], v[154:157], v[192:195], 0
	v_mfma_i32_16x16x64_i8 v[110:113], v[150:153], v[168:171], v[110:113]
	v_mfma_i32_16x16x64_i8 v[106:109], v[160:163], v[168:171], v[106:109]
	v_mfma_i32_16x16x64_i8 v[94:97], v[150:153], v[180:183], v[94:97]
	v_mfma_i32_16x16x64_i8 v[90:93], v[160:163], v[180:183], v[90:93]
	v_mfma_i32_16x16x64_i8 v[78:81], v[150:153], v[188:191], v[78:81]
	v_mfma_i32_16x16x64_i8 v[74:77], v[160:163], v[188:191], v[74:77]
	v_mfma_i32_16x16x64_i8 v[70:73], v[150:153], v[196:199], v[70:73]
	v_mfma_i32_16x16x64_i8 v[66:69], v[160:163], v[196:199], v[66:69]
	s_barrier
	s_mov_b64 s[76:77], s[44:45]
	ds_read_b128 v[164:167], v200 offset:16384
	ds_read_b128 v[168:171], v200 offset:17408
	ds_read_b128 v[172:175], v200 offset:18432
	ds_read_b128 v[180:183], v200 offset:19456
	ds_read_b128 v[184:187], v200 offset:20480
	ds_read_b128 v[188:191], v200 offset:21504
	ds_read_b128 v[192:195], v200 offset:22528
	ds_read_b128 v[196:199], v200 offset:23552
	s_add_i32 s29, s29, s48
	v_lshl_add_u64 v[176:177], s[76:77], 0, v[202:203]
	s_add_u32 s76, s76, 0x30000
	s_mov_b32 m0, s29
	s_addc_u32 s77, s77, 0
	global_load_lds_dwordx4 v[176:177], off
	s_add_i32 m0, s29, 0x2000
	v_lshl_add_u64 v[176:177], s[76:77], 0, v[202:203]
	s_add_u32 s76, s44, 0x60000
	s_addc_u32 s77, s45, 0
	global_load_lds_dwordx4 v[176:177], off
	s_add_i32 s29, s78, s48
	v_lshl_add_u64 v[176:177], s[76:77], 0, v[202:203]
	s_add_u32 s76, s76, 0x30000
	s_mov_b32 m0, s29
	s_addc_u32 s77, s77, 0
	global_load_lds_dwordx4 v[176:177], off
	s_add_i32 m0, s29, 0x2000
	v_lshl_add_u64 v[176:177], s[76:77], 0, v[202:203]
	s_mov_b64 s[76:77], s[46:47]
	global_load_lds_dwordx4 v[176:177], off
	s_mov_b32 m0, s49
	v_lshl_add_u64 v[176:177], s[76:77], 0, v[158:159]
	s_add_u32 s76, s76, 0x40000
	s_addc_u32 s77, s77, 0
	global_load_lds_dwordx4 v[176:177], off
	s_mov_b32 m0, s50
	v_lshl_add_u64 v[176:177], s[76:77], 0, v[158:159]
	global_load_lds_dwordx4 v[176:177], off
	s_waitcnt vmcnt(8)
	s_waitcnt lgkmcnt(0)
	s_barrier
	v_mfma_i32_16x16x64_i8 v[62:65], v[130:133], v[164:167], 0
	v_mfma_i32_16x16x64_i8 v[58:61], v[138:141], v[164:167], 0
	v_mfma_i32_16x16x64_i8 v[54:57], v[130:133], v[172:175], 0
	v_mfma_i32_16x16x64_i8 v[50:53], v[138:141], v[172:175], 0
	v_mfma_i32_16x16x64_i8 v[38:41], v[130:133], v[184:187], 0
	v_mfma_i32_16x16x64_i8 v[34:37], v[138:141], v[184:187], 0
	v_mfma_i32_16x16x64_i8 v[14:17], v[130:133], v[192:195], 0
	v_mfma_i32_16x16x64_i8 v[10:13], v[138:141], v[192:195], 0
	v_mfma_i32_16x16x64_i8 v[62:65], v[134:137], v[168:171], v[62:65]
	v_mfma_i32_16x16x64_i8 v[58:61], v[142:145], v[168:171], v[58:61]
	v_mfma_i32_16x16x64_i8 v[54:57], v[134:137], v[180:183], v[54:57]
	v_mfma_i32_16x16x64_i8 v[50:53], v[142:145], v[180:183], v[50:53]
	v_mfma_i32_16x16x64_i8 v[38:41], v[134:137], v[188:191], v[38:41]
	v_mfma_i32_16x16x64_i8 v[34:37], v[142:145], v[188:191], v[34:37]
	v_mfma_i32_16x16x64_i8 v[14:17], v[134:137], v[196:199], v[14:17]
	v_mfma_i32_16x16x64_i8 v[10:13], v[142:145], v[196:199], v[10:13]
	v_mfma_i32_16x16x64_i8 v[46:49], v[146:149], v[164:167], 0
	v_mfma_i32_16x16x64_i8 v[42:45], v[154:157], v[164:167], 0
	v_mfma_i32_16x16x64_i8 v[30:33], v[146:149], v[172:175], 0
	v_mfma_i32_16x16x64_i8 v[26:29], v[154:157], v[172:175], 0
	v_mfma_i32_16x16x64_i8 v[22:25], v[146:149], v[184:187], 0
	v_mfma_i32_16x16x64_i8 v[18:21], v[154:157], v[184:187], 0
	v_mfma_i32_16x16x64_i8 v[6:9], v[146:149], v[192:195], v[6:9]
	v_mfma_i32_16x16x64_i8 v[2:5], v[154:157], v[192:195], v[2:5]
	v_mfma_i32_16x16x64_i8 v[46:49], v[150:153], v[168:171], v[46:49]
	v_mfma_i32_16x16x64_i8 v[42:45], v[160:163], v[168:171], v[42:45]
	v_mfma_i32_16x16x64_i8 v[30:33], v[150:153], v[180:183], v[30:33]
	v_mfma_i32_16x16x64_i8 v[26:29], v[160:163], v[180:183], v[26:29]
	v_mfma_i32_16x16x64_i8 v[22:25], v[150:153], v[188:191], v[22:25]
	v_mfma_i32_16x16x64_i8 v[18:21], v[160:163], v[188:191], v[18:21]
	v_mfma_i32_16x16x64_i8 v[6:9], v[150:153], v[196:199], v[6:9]
	v_mfma_i32_16x16x64_i8 v[2:5], v[160:163], v[196:199], v[2:5]
	s_barrier
	s_add_i32 s29, 0, 0x18000
	s_add_i32 s76, 0, 0x1c000
	v_add_u32_e32 v142, s29, v179
	v_add_u32_e32 v160, s76, v179
	ds_read_b128 v[130:133], v142
	ds_read_b128 v[134:137], v142 offset:1024
	ds_read_b128 v[138:141], v142 offset:2048
	ds_read_b128 v[142:145], v142 offset:3072
	ds_read_b128 v[146:149], v160
	ds_read_b128 v[150:153], v160 offset:1024
	ds_read_b128 v[154:157], v160 offset:2048
	ds_read_b128 v[160:163], v160 offset:3072
	s_add_u32 s46, s46, 0x80000
	s_addc_u32 s47, s47, 0
	ds_read_b128 v[164:167], v200 offset:32768
	ds_read_b128 v[168:171], v200 offset:33792
	ds_read_b128 v[172:175], v200 offset:34816
	ds_read_b128 v[180:183], v200 offset:35840
	ds_read_b128 v[184:187], v200 offset:36864
	ds_read_b128 v[188:191], v200 offset:37888
	ds_read_b128 v[192:195], v200 offset:38912
	ds_read_b128 v[196:199], v200 offset:39936
	s_mov_b32 m0, s51
	v_lshl_add_u64 v[176:177], s[46:47], 0, v[158:159]
	s_add_u32 s46, s46, 0x40000
	s_addc_u32 s47, s47, 0
	global_load_lds_dwordx4 v[176:177], off
	s_mov_b32 m0, s52
	v_lshl_add_u64 v[176:177], s[46:47], 0, v[158:159]
	global_load_lds_dwordx4 v[176:177], off
	s_waitcnt vmcnt(8)
	s_waitcnt lgkmcnt(0)
	s_barrier
	v_mfma_i32_16x16x64_i8 v[126:129], v[130:133], v[164:167], v[126:129]
	v_mfma_i32_16x16x64_i8 v[122:125], v[138:141], v[164:167], v[122:125]
	v_mfma_i32_16x16x64_i8 v[118:121], v[130:133], v[172:175], v[118:121]
	v_mfma_i32_16x16x64_i8 v[114:117], v[138:141], v[172:175], v[114:117]
	v_mfma_i32_16x16x64_i8 v[102:105], v[130:133], v[184:187], v[102:105]
	v_mfma_i32_16x16x64_i8 v[98:101], v[138:141], v[184:187], v[98:101]
	v_mfma_i32_16x16x64_i8 v[86:89], v[130:133], v[192:195], v[86:89]
	v_mfma_i32_16x16x64_i8 v[82:85], v[138:141], v[192:195], v[82:85]
	v_mfma_i32_16x16x64_i8 v[126:129], v[134:137], v[168:171], v[126:129]
	v_mfma_i32_16x16x64_i8 v[122:125], v[142:145], v[168:171], v[122:125]
	v_mfma_i32_16x16x64_i8 v[118:121], v[134:137], v[180:183], v[118:121]
	v_mfma_i32_16x16x64_i8 v[114:117], v[142:145], v[180:183], v[114:117]
	v_mfma_i32_16x16x64_i8 v[102:105], v[134:137], v[188:191], v[102:105]
	v_mfma_i32_16x16x64_i8 v[98:101], v[142:145], v[188:191], v[98:101]
	v_mfma_i32_16x16x64_i8 v[86:89], v[134:137], v[196:199], v[86:89]
	v_mfma_i32_16x16x64_i8 v[82:85], v[142:145], v[196:199], v[82:85]
	v_mfma_i32_16x16x64_i8 v[110:113], v[146:149], v[164:167], v[110:113]
	v_mfma_i32_16x16x64_i8 v[106:109], v[154:157], v[164:167], v[106:109]
	v_mfma_i32_16x16x64_i8 v[94:97], v[146:149], v[172:175], v[94:97]
	v_mfma_i32_16x16x64_i8 v[90:93], v[154:157], v[172:175], v[90:93]
	v_mfma_i32_16x16x64_i8 v[78:81], v[146:149], v[184:187], v[78:81]
	v_mfma_i32_16x16x64_i8 v[74:77], v[154:157], v[184:187], v[74:77]
	v_mfma_i32_16x16x64_i8 v[70:73], v[146:149], v[192:195], v[70:73]
	v_mfma_i32_16x16x64_i8 v[66:69], v[154:157], v[192:195], v[66:69]
	v_mfma_i32_16x16x64_i8 v[110:113], v[150:153], v[168:171], v[110:113]
	v_mfma_i32_16x16x64_i8 v[106:109], v[160:163], v[168:171], v[106:109]
	v_mfma_i32_16x16x64_i8 v[94:97], v[150:153], v[180:183], v[94:97]
	v_mfma_i32_16x16x64_i8 v[90:93], v[160:163], v[180:183], v[90:93]
	v_mfma_i32_16x16x64_i8 v[78:81], v[150:153], v[188:191], v[78:81]
	v_mfma_i32_16x16x64_i8 v[74:77], v[160:163], v[188:191], v[74:77]
	v_mfma_i32_16x16x64_i8 v[70:73], v[150:153], v[196:199], v[70:73]
	v_mfma_i32_16x16x64_i8 v[66:69], v[160:163], v[196:199], v[66:69]
	s_barrier
	s_add_u32 s46, s44, 0x80
	s_addc_u32 s47, s45, 0
	ds_read_b128 v[164:167], v200 offset:49152
	ds_read_b128 v[168:171], v200 offset:50176
	ds_read_b128 v[172:175], v200 offset:51200
	ds_read_b128 v[180:183], v200 offset:52224
	ds_read_b128 v[184:187], v200 offset:53248
	ds_read_b128 v[188:191], v200 offset:54272
	ds_read_b128 v[192:195], v200 offset:55296
	ds_read_b128 v[196:199], v200 offset:56320
	s_add_i32 s29, s29, s48
	v_lshl_add_u64 v[176:177], s[46:47], 0, v[202:203]
	s_mov_b32 m0, s29
	s_add_u32 s46, s46, 0x30000
	global_load_lds_dwordx4 v[176:177], off
	s_addc_u32 s47, s47, 0
	s_add_i32 m0, s29, 0x2000
	s_add_u32 s44, s44, 0x60080
	s_addc_u32 s45, s45, 0
	v_lshl_add_u64 v[176:177], s[46:47], 0, v[202:203]
	global_load_lds_dwordx4 v[176:177], off
	s_add_i32 s29, s76, s48
	v_lshl_add_u64 v[176:177], s[44:45], 0, v[202:203]
	s_add_u32 s44, s44, 0x30000
	s_mov_b32 m0, s29
	s_addc_u32 s45, s45, 0
	global_load_lds_dwordx4 v[176:177], off
	s_add_i32 m0, s29, 0x2000
	v_lshl_add_u64 v[176:177], s[44:45], 0, v[202:203]
	global_load_lds_dwordx4 v[176:177], off
	s_mov_b32 m0, s53
	v_lshl_add_u64 v[176:177], s[10:11], 0, v[158:159]
	s_add_u32 s10, s10, 0x40000
	s_addc_u32 s11, s11, 0
	global_load_lds_dwordx4 v[176:177], off
	s_mov_b32 m0, s54
	v_lshl_add_u64 v[176:177], s[10:11], 0, v[158:159]
	global_load_lds_dwordx4 v[176:177], off
	s_waitcnt vmcnt(8)
	s_waitcnt lgkmcnt(0)
	s_barrier
	v_mfma_i32_16x16x64_i8 v[62:65], v[130:133], v[164:167], v[62:65]
	v_mfma_i32_16x16x64_i8 v[58:61], v[138:141], v[164:167], v[58:61]
	v_mfma_i32_16x16x64_i8 v[54:57], v[130:133], v[172:175], v[54:57]
	v_mfma_i32_16x16x64_i8 v[50:53], v[138:141], v[172:175], v[50:53]
	v_mfma_i32_16x16x64_i8 v[38:41], v[130:133], v[184:187], v[38:41]
	v_mfma_i32_16x16x64_i8 v[34:37], v[138:141], v[184:187], v[34:37]
	v_mfma_i32_16x16x64_i8 v[14:17], v[130:133], v[192:195], v[14:17]
	v_mfma_i32_16x16x64_i8 v[10:13], v[138:141], v[192:195], v[10:13]
	v_mfma_i32_16x16x64_i8 v[62:65], v[134:137], v[168:171], v[62:65]
	v_mfma_i32_16x16x64_i8 v[58:61], v[142:145], v[168:171], v[58:61]
	v_mfma_i32_16x16x64_i8 v[54:57], v[134:137], v[180:183], v[54:57]
	v_mfma_i32_16x16x64_i8 v[50:53], v[142:145], v[180:183], v[50:53]
	v_mfma_i32_16x16x64_i8 v[38:41], v[134:137], v[188:191], v[38:41]
	v_mfma_i32_16x16x64_i8 v[34:37], v[142:145], v[188:191], v[34:37]
	v_mfma_i32_16x16x64_i8 v[14:17], v[134:137], v[196:199], v[14:17]
	v_mfma_i32_16x16x64_i8 v[10:13], v[142:145], v[196:199], v[10:13]
	v_mfma_i32_16x16x64_i8 v[46:49], v[146:149], v[164:167], v[46:49]
	v_mfma_i32_16x16x64_i8 v[42:45], v[154:157], v[164:167], v[42:45]
	v_mfma_i32_16x16x64_i8 v[30:33], v[146:149], v[172:175], v[30:33]
	v_mfma_i32_16x16x64_i8 v[26:29], v[154:157], v[172:175], v[26:29]
	v_mfma_i32_16x16x64_i8 v[22:25], v[146:149], v[184:187], v[22:25]
	v_mfma_i32_16x16x64_i8 v[18:21], v[154:157], v[184:187], v[18:21]
	v_mfma_i32_16x16x64_i8 v[6:9], v[146:149], v[192:195], v[6:9]
	v_mfma_i32_16x16x64_i8 v[2:5], v[154:157], v[192:195], v[2:5]
	v_mfma_i32_16x16x64_i8 v[46:49], v[150:153], v[168:171], v[46:49]
	v_mfma_i32_16x16x64_i8 v[42:45], v[160:163], v[168:171], v[42:45]
	v_mfma_i32_16x16x64_i8 v[30:33], v[150:153], v[180:183], v[30:33]
	v_mfma_i32_16x16x64_i8 v[26:29], v[160:163], v[180:183], v[26:29]
	v_mfma_i32_16x16x64_i8 v[22:25], v[150:153], v[188:191], v[22:25]
	v_mfma_i32_16x16x64_i8 v[18:21], v[160:163], v[188:191], v[18:21]
	v_mfma_i32_16x16x64_i8 v[6:9], v[150:153], v[196:199], v[6:9]
	v_mfma_i32_16x16x64_i8 v[2:5], v[160:163], v[196:199], v[2:5]
	s_barrier
	s_add_u32 s74, s74, 0x100
	s_addc_u32 s75, s75, 0
	s_add_u32 s72, s72, 0x100
	s_addc_u32 s73, s73, 0
	s_cmp_ge_i32 s28, s69
	s_mov_b32 s10, s28
	s_cbranch_scc1 .Lpeel2_exit

.LBB0_1213:
	s_add_u32 s23, s48, 0x100
	s_addc_u32 s62, s49, 0
	s_add_u32 s63, s46, 0x100
	v_mov_b32_e32 v2, 0
	s_addc_u32 s64, s47, 0
	s_mov_b32 s65, -2
	v_mov_b32_e32 v3, 0
	v_mov_b64_e32 v[4:5], 0
	s_cmp_eq_u32 s65, 12
	s_cselect_b32 s50, s42, s23
	s_cselect_b32 s51, s43, s62
	s_cselect_b32 s48, s44, s63
	s_cselect_b32 s49, s45, s64
	s_add_u32 s46, s50, 0x80
	s_addc_u32 s47, s51, 0
	s_add_i32 s68, 0, 0x10000
	s_add_i32 s69, 0, 0x14000
	v_add_u32_e32 v142, s68, v208
	v_add_u32_e32 v158, s69, v208
	ds_read_b128 v[130:133], v142
	ds_read_b128 v[134:137], v142 offset:1024
	ds_read_b128 v[138:141], v142 offset:2048
	ds_read_b128 v[142:145], v142 offset:3072
	ds_read_b128 v[146:149], v158
	ds_read_b128 v[150:153], v158 offset:1024
	ds_read_b128 v[154:157], v158 offset:2048
	ds_read_b128 v[158:161], v158 offset:3072
	s_add_u32 s66, s23, 0x7ff80
	s_addc_u32 s67, s62, 0
	ds_read_b128 v[162:165], v210
	ds_read_b128 v[166:169], v210 offset:1024
	ds_read_b128 v[170:173], v210 offset:2048
	ds_read_b128 v[174:177], v210 offset:3072
	ds_read_b128 v[180:183], v210 offset:4096
	ds_read_b128 v[184:187], v210 offset:5120
	ds_read_b128 v[188:191], v210 offset:6144
	ds_read_b128 v[192:195], v210 offset:7168
	s_add_i32 m0, s52, 0xc000
	v_lshl_add_u64 v[196:197], s[66:67], 0, v[178:179]
	s_add_u32 s66, s66, 0x40000
	s_addc_u32 s67, s67, 0
	global_load_lds_dwordx4 v[196:197], off
	s_add_i32 m0, s52, 0xe000
	v_lshl_add_u64 v[196:197], s[66:67], 0, v[178:179]
	global_load_lds_dwordx4 v[196:197], off
	s_waitcnt vmcnt(8)
	s_waitcnt lgkmcnt(0)
	s_barrier
	v_mfma_i32_16x16x64_i8 v[126:129], v[130:133], v[162:165], 0
	v_mfma_i32_16x16x64_i8 v[118:121], v[138:141], v[162:165], 0
	v_mfma_i32_16x16x64_i8 v[110:113], v[130:133], v[170:173], 0
	v_mfma_i32_16x16x64_i8 v[102:105], v[138:141], v[170:173], 0
	v_mfma_i32_16x16x64_i8 v[94:97], v[130:133], v[180:183], 0
	v_mfma_i32_16x16x64_i8 v[86:89], v[138:141], v[180:183], 0
	v_mfma_i32_16x16x64_i8 v[78:81], v[130:133], v[188:191], 0
	v_mfma_i32_16x16x64_i8 v[70:73], v[138:141], v[188:191], 0
	v_mfma_i32_16x16x64_i8 v[126:129], v[134:137], v[166:169], v[126:129]
	v_mfma_i32_16x16x64_i8 v[118:121], v[142:145], v[166:169], v[118:121]
	v_mfma_i32_16x16x64_i8 v[110:113], v[134:137], v[174:177], v[110:113]
	v_mfma_i32_16x16x64_i8 v[102:105], v[142:145], v[174:177], v[102:105]
	v_mfma_i32_16x16x64_i8 v[94:97], v[134:137], v[184:187], v[94:97]
	v_mfma_i32_16x16x64_i8 v[86:89], v[142:145], v[184:187], v[86:89]
	v_mfma_i32_16x16x64_i8 v[78:81], v[134:137], v[192:195], v[78:81]
	v_mfma_i32_16x16x64_i8 v[70:73], v[142:145], v[192:195], v[70:73]
	v_mfma_i32_16x16x64_i8 v[122:125], v[146:149], v[162:165], 0
	v_mfma_i32_16x16x64_i8 v[114:117], v[154:157], v[162:165], 0
	v_mfma_i32_16x16x64_i8 v[106:109], v[146:149], v[170:173], 0
	v_mfma_i32_16x16x64_i8 v[98:101], v[154:157], v[170:173], 0
	v_mfma_i32_16x16x64_i8 v[90:93], v[146:149], v[180:183], 0
	v_mfma_i32_16x16x64_i8 v[82:85], v[154:157], v[180:183], 0
	v_mfma_i32_16x16x64_i8 v[74:77], v[146:149], v[188:191], 0
	v_mfma_i32_16x16x64_i8 v[66:69], v[154:157], v[188:191], 0
	v_mfma_i32_16x16x64_i8 v[122:125], v[150:153], v[166:169], v[122:125]
	v_mfma_i32_16x16x64_i8 v[114:117], v[158:161], v[166:169], v[114:117]
	v_mfma_i32_16x16x64_i8 v[106:109], v[150:153], v[174:177], v[106:109]
	v_mfma_i32_16x16x64_i8 v[98:101], v[158:161], v[174:177], v[98:101]
	v_mfma_i32_16x16x64_i8 v[90:93], v[150:153], v[184:187], v[90:93]
	v_mfma_i32_16x16x64_i8 v[82:85], v[158:161], v[184:187], v[82:85]
	v_mfma_i32_16x16x64_i8 v[74:77], v[150:153], v[192:195], v[74:77]
	v_mfma_i32_16x16x64_i8 v[66:69], v[158:161], v[192:195], v[66:69]
	s_barrier
	s_mov_b64 s[66:67], s[48:49]
	ds_read_b128 v[162:165], v210 offset:16384
	ds_read_b128 v[166:169], v210 offset:17408
	ds_read_b128 v[170:173], v210 offset:18432
	ds_read_b128 v[174:177], v210 offset:19456
	ds_read_b128 v[180:183], v210 offset:20480
	ds_read_b128 v[184:187], v210 offset:21504
	ds_read_b128 v[188:191], v210 offset:22528
	ds_read_b128 v[192:195], v210 offset:23552
	s_add_i32 s68, s68, s31
	v_lshl_add_u64 v[196:197], s[66:67], 0, v[202:203]
	s_add_u32 s66, s66, 0x20000
	s_mov_b32 m0, s68
	s_addc_u32 s67, s67, 0
	global_load_lds_dwordx4 v[196:197], off
	s_add_i32 m0, s68, 0x2000
	v_lshl_add_u64 v[196:197], s[66:67], 0, v[202:203]
	s_add_u32 s66, s48, 0x40000
	s_addc_u32 s67, s49, 0
	global_load_lds_dwordx4 v[196:197], off
	s_add_i32 s68, s69, s31
	v_lshl_add_u64 v[196:197], s[66:67], 0, v[202:203]
	s_add_u32 s66, s66, 0x20000
	s_mov_b32 m0, s68
	s_addc_u32 s67, s67, 0
	global_load_lds_dwordx4 v[196:197], off
	s_add_i32 m0, s68, 0x2000
	v_lshl_add_u64 v[196:197], s[66:67], 0, v[202:203]
	s_mov_b64 s[66:67], s[50:51]
	global_load_lds_dwordx4 v[196:197], off
	s_mov_b32 m0, s52
	v_lshl_add_u64 v[196:197], s[66:67], 0, v[178:179]
	s_add_u32 s66, s66, 0x40000
	s_addc_u32 s67, s67, 0
	global_load_lds_dwordx4 v[196:197], off
	s_mov_b32 m0, s53
	v_lshl_add_u64 v[196:197], s[66:67], 0, v[178:179]
	global_load_lds_dwordx4 v[196:197], off
	s_waitcnt vmcnt(8)
	s_waitcnt lgkmcnt(0)
	s_barrier
	v_mfma_i32_16x16x64_i8 v[62:65], v[130:133], v[162:165], 0
	v_mfma_i32_16x16x64_i8 v[54:57], v[138:141], v[162:165], 0
	v_mfma_i32_16x16x64_i8 v[46:49], v[130:133], v[170:173], 0
	v_mfma_i32_16x16x64_i8 v[38:41], v[138:141], v[170:173], 0
	v_mfma_i32_16x16x64_i8 v[30:33], v[130:133], v[180:183], 0
	v_mfma_i32_16x16x64_i8 v[22:25], v[138:141], v[180:183], 0
	v_mfma_i32_16x16x64_i8 v[14:17], v[130:133], v[188:191], 0
	v_mfma_i32_16x16x64_i8 v[6:9], v[138:141], v[188:191], 0
	v_mfma_i32_16x16x64_i8 v[62:65], v[134:137], v[166:169], v[62:65]
	v_mfma_i32_16x16x64_i8 v[54:57], v[142:145], v[166:169], v[54:57]
	v_mfma_i32_16x16x64_i8 v[46:49], v[134:137], v[174:177], v[46:49]
	v_mfma_i32_16x16x64_i8 v[38:41], v[142:145], v[174:177], v[38:41]
	v_mfma_i32_16x16x64_i8 v[30:33], v[134:137], v[184:187], v[30:33]
	v_mfma_i32_16x16x64_i8 v[22:25], v[142:145], v[184:187], v[22:25]
	v_mfma_i32_16x16x64_i8 v[14:17], v[134:137], v[192:195], v[14:17]
	v_mfma_i32_16x16x64_i8 v[6:9], v[142:145], v[192:195], v[6:9]
	v_mfma_i32_16x16x64_i8 v[58:61], v[146:149], v[162:165], 0
	v_mfma_i32_16x16x64_i8 v[50:53], v[154:157], v[162:165], 0
	v_mfma_i32_16x16x64_i8 v[42:45], v[146:149], v[170:173], 0
	v_mfma_i32_16x16x64_i8 v[34:37], v[154:157], v[170:173], 0
	v_mfma_i32_16x16x64_i8 v[26:29], v[146:149], v[180:183], 0
	v_mfma_i32_16x16x64_i8 v[18:21], v[154:157], v[180:183], 0
	v_mfma_i32_16x16x64_i8 v[10:13], v[146:149], v[188:191], 0
	v_mfma_i32_16x16x64_i8 v[2:5], v[154:157], v[188:191], v[2:5]
	v_mfma_i32_16x16x64_i8 v[58:61], v[150:153], v[166:169], v[58:61]
	v_mfma_i32_16x16x64_i8 v[50:53], v[158:161], v[166:169], v[50:53]
	v_mfma_i32_16x16x64_i8 v[42:45], v[150:153], v[174:177], v[42:45]
	v_mfma_i32_16x16x64_i8 v[34:37], v[158:161], v[174:177], v[34:37]
	v_mfma_i32_16x16x64_i8 v[26:29], v[150:153], v[184:187], v[26:29]
	v_mfma_i32_16x16x64_i8 v[18:21], v[158:161], v[184:187], v[18:21]
	v_mfma_i32_16x16x64_i8 v[10:13], v[150:153], v[192:195], v[10:13]
	v_mfma_i32_16x16x64_i8 v[2:5], v[158:161], v[192:195], v[2:5]
	s_barrier
	s_add_i32 s66, 0, 0x18000
	s_add_i32 s67, 0, 0x1c000
	v_add_u32_e32 v142, s66, v208
	v_add_u32_e32 v158, s67, v208
	ds_read_b128 v[130:133], v142
	ds_read_b128 v[134:137], v142 offset:1024
	ds_read_b128 v[138:141], v142 offset:2048
	ds_read_b128 v[142:145], v142 offset:3072
	ds_read_b128 v[146:149], v158
	ds_read_b128 v[150:153], v158 offset:1024
	ds_read_b128 v[154:157], v158 offset:2048
	ds_read_b128 v[158:161], v158 offset:3072
	s_add_u32 s50, s50, 0x80000
	s_addc_u32 s51, s51, 0
	ds_read_b128 v[162:165], v210 offset:32768
	ds_read_b128 v[166:169], v210 offset:33792
	ds_read_b128 v[170:173], v210 offset:34816
	ds_read_b128 v[174:177], v210 offset:35840
	ds_read_b128 v[180:183], v210 offset:36864
	ds_read_b128 v[184:187], v210 offset:37888
	ds_read_b128 v[188:191], v210 offset:38912
	ds_read_b128 v[192:195], v210 offset:39936
	s_mov_b32 m0, s54
	v_lshl_add_u64 v[196:197], s[50:51], 0, v[178:179]
	s_add_u32 s50, s50, 0x40000
	s_addc_u32 s51, s51, 0
	global_load_lds_dwordx4 v[196:197], off
	s_mov_b32 m0, s55
	v_lshl_add_u64 v[196:197], s[50:51], 0, v[178:179]
	global_load_lds_dwordx4 v[196:197], off
	s_waitcnt vmcnt(8)
	s_waitcnt lgkmcnt(0)
	s_barrier
	v_mfma_i32_16x16x64_i8 v[126:129], v[130:133], v[162:165], v[126:129]
	v_mfma_i32_16x16x64_i8 v[118:121], v[138:141], v[162:165], v[118:121]
	v_mfma_i32_16x16x64_i8 v[110:113], v[130:133], v[170:173], v[110:113]
	v_mfma_i32_16x16x64_i8 v[102:105], v[138:141], v[170:173], v[102:105]
	v_mfma_i32_16x16x64_i8 v[94:97], v[130:133], v[180:183], v[94:97]
	v_mfma_i32_16x16x64_i8 v[86:89], v[138:141], v[180:183], v[86:89]
	v_mfma_i32_16x16x64_i8 v[78:81], v[130:133], v[188:191], v[78:81]
	v_mfma_i32_16x16x64_i8 v[70:73], v[138:141], v[188:191], v[70:73]
	v_mfma_i32_16x16x64_i8 v[126:129], v[134:137], v[166:169], v[126:129]
	v_mfma_i32_16x16x64_i8 v[118:121], v[142:145], v[166:169], v[118:121]
	v_mfma_i32_16x16x64_i8 v[110:113], v[134:137], v[174:177], v[110:113]
	v_mfma_i32_16x16x64_i8 v[102:105], v[142:145], v[174:177], v[102:105]
	v_mfma_i32_16x16x64_i8 v[94:97], v[134:137], v[184:187], v[94:97]
	v_mfma_i32_16x16x64_i8 v[86:89], v[142:145], v[184:187], v[86:89]
	v_mfma_i32_16x16x64_i8 v[78:81], v[134:137], v[192:195], v[78:81]
	v_mfma_i32_16x16x64_i8 v[70:73], v[142:145], v[192:195], v[70:73]
	v_mfma_i32_16x16x64_i8 v[122:125], v[146:149], v[162:165], v[122:125]
	v_mfma_i32_16x16x64_i8 v[114:117], v[154:157], v[162:165], v[114:117]
	v_mfma_i32_16x16x64_i8 v[106:109], v[146:149], v[170:173], v[106:109]
	v_mfma_i32_16x16x64_i8 v[98:101], v[154:157], v[170:173], v[98:101]
	v_mfma_i32_16x16x64_i8 v[90:93], v[146:149], v[180:183], v[90:93]
	v_mfma_i32_16x16x64_i8 v[82:85], v[154:157], v[180:183], v[82:85]
	v_mfma_i32_16x16x64_i8 v[74:77], v[146:149], v[188:191], v[74:77]
	v_mfma_i32_16x16x64_i8 v[66:69], v[154:157], v[188:191], v[66:69]
	v_mfma_i32_16x16x64_i8 v[122:125], v[150:153], v[166:169], v[122:125]
	v_mfma_i32_16x16x64_i8 v[114:117], v[158:161], v[166:169], v[114:117]
	v_mfma_i32_16x16x64_i8 v[106:109], v[150:153], v[174:177], v[106:109]
	v_mfma_i32_16x16x64_i8 v[98:101], v[158:161], v[174:177], v[98:101]
	v_mfma_i32_16x16x64_i8 v[90:93], v[150:153], v[184:187], v[90:93]
	v_mfma_i32_16x16x64_i8 v[82:85], v[158:161], v[184:187], v[82:85]
	v_mfma_i32_16x16x64_i8 v[74:77], v[150:153], v[192:195], v[74:77]
	v_mfma_i32_16x16x64_i8 v[66:69], v[158:161], v[192:195], v[66:69]
	s_barrier
	s_add_u32 s50, s48, 0x80
	s_addc_u32 s51, s49, 0
	ds_read_b128 v[162:165], v210 offset:49152
	ds_read_b128 v[166:169], v210 offset:50176
	ds_read_b128 v[170:173], v210 offset:51200
	ds_read_b128 v[174:177], v210 offset:52224
	ds_read_b128 v[180:183], v210 offset:53248
	ds_read_b128 v[184:187], v210 offset:54272
	ds_read_b128 v[188:191], v210 offset:55296
	ds_read_b128 v[192:195], v210 offset:56320
	s_add_i32 s66, s66, s31
	v_lshl_add_u64 v[196:197], s[50:51], 0, v[202:203]
	s_mov_b32 m0, s66
	s_add_u32 s50, s50, 0x20000
	global_load_lds_dwordx4 v[196:197], off
	s_addc_u32 s51, s51, 0
	s_add_i32 m0, s66, 0x2000
	s_add_u32 s48, s48, 0x40080
	s_addc_u32 s49, s49, 0
	v_lshl_add_u64 v[196:197], s[50:51], 0, v[202:203]
	global_load_lds_dwordx4 v[196:197], off
	s_add_i32 s50, s67, s31
	v_lshl_add_u64 v[196:197], s[48:49], 0, v[202:203]
	s_add_u32 s48, s48, 0x20000
	s_mov_b32 m0, s50
	s_addc_u32 s49, s49, 0
	global_load_lds_dwordx4 v[196:197], off
	s_add_i32 m0, s50, 0x2000
	v_lshl_add_u64 v[196:197], s[48:49], 0, v[202:203]
	global_load_lds_dwordx4 v[196:197], off
	s_mov_b32 m0, s56
	v_lshl_add_u64 v[196:197], s[46:47], 0, v[178:179]
	s_add_u32 s46, s46, 0x40000
	s_addc_u32 s47, s47, 0
	global_load_lds_dwordx4 v[196:197], off
	s_mov_b32 m0, s57
	v_lshl_add_u64 v[196:197], s[46:47], 0, v[178:179]
	global_load_lds_dwordx4 v[196:197], off
	s_waitcnt vmcnt(8)
	s_waitcnt lgkmcnt(0)
	s_barrier
	v_mfma_i32_16x16x64_i8 v[62:65], v[130:133], v[162:165], v[62:65]
	v_mfma_i32_16x16x64_i8 v[54:57], v[138:141], v[162:165], v[54:57]
	v_mfma_i32_16x16x64_i8 v[46:49], v[130:133], v[170:173], v[46:49]
	v_mfma_i32_16x16x64_i8 v[38:41], v[138:141], v[170:173], v[38:41]
	v_mfma_i32_16x16x64_i8 v[30:33], v[130:133], v[180:183], v[30:33]
	v_mfma_i32_16x16x64_i8 v[22:25], v[138:141], v[180:183], v[22:25]
	v_mfma_i32_16x16x64_i8 v[14:17], v[130:133], v[188:191], v[14:17]
	v_mfma_i32_16x16x64_i8 v[6:9], v[138:141], v[188:191], v[6:9]
	v_mfma_i32_16x16x64_i8 v[62:65], v[134:137], v[166:169], v[62:65]
	v_mfma_i32_16x16x64_i8 v[54:57], v[142:145], v[166:169], v[54:57]
	v_mfma_i32_16x16x64_i8 v[46:49], v[134:137], v[174:177], v[46:49]
	v_mfma_i32_16x16x64_i8 v[38:41], v[142:145], v[174:177], v[38:41]
	v_mfma_i32_16x16x64_i8 v[30:33], v[134:137], v[184:187], v[30:33]
	v_mfma_i32_16x16x64_i8 v[22:25], v[142:145], v[184:187], v[22:25]
	v_mfma_i32_16x16x64_i8 v[14:17], v[134:137], v[192:195], v[14:17]
	v_mfma_i32_16x16x64_i8 v[6:9], v[142:145], v[192:195], v[6:9]
	v_mfma_i32_16x16x64_i8 v[58:61], v[146:149], v[162:165], v[58:61]
	v_mfma_i32_16x16x64_i8 v[50:53], v[154:157], v[162:165], v[50:53]
	v_mfma_i32_16x16x64_i8 v[42:45], v[146:149], v[170:173], v[42:45]
	v_mfma_i32_16x16x64_i8 v[34:37], v[154:157], v[170:173], v[34:37]
	v_mfma_i32_16x16x64_i8 v[26:29], v[146:149], v[180:183], v[26:29]
	v_mfma_i32_16x16x64_i8 v[18:21], v[154:157], v[180:183], v[18:21]
	v_mfma_i32_16x16x64_i8 v[10:13], v[146:149], v[188:191], v[10:13]
	v_mfma_i32_16x16x64_i8 v[2:5], v[154:157], v[188:191], v[2:5]
	v_mfma_i32_16x16x64_i8 v[58:61], v[150:153], v[166:169], v[58:61]
	v_mfma_i32_16x16x64_i8 v[50:53], v[158:161], v[166:169], v[50:53]
	v_mfma_i32_16x16x64_i8 v[42:45], v[150:153], v[174:177], v[42:45]
	v_mfma_i32_16x16x64_i8 v[34:37], v[158:161], v[174:177], v[34:37]
	v_mfma_i32_16x16x64_i8 v[26:29], v[150:153], v[184:187], v[26:29]
	v_mfma_i32_16x16x64_i8 v[18:21], v[158:161], v[184:187], v[18:21]
	v_mfma_i32_16x16x64_i8 v[10:13], v[150:153], v[192:195], v[10:13]
	v_mfma_i32_16x16x64_i8 v[2:5], v[158:161], v[192:195], v[2:5]
	s_barrier
	s_add_i32 s65, s65, 2
	s_add_u32 s23, s23, 0x100
	s_addc_u32 s62, s62, 0
	s_add_u32 s63, s63, 0x100
	s_addc_u32 s64, s64, 0
	s_cmp_gt_u32 s65, 13
	s_cbranch_scc1 .Lpeel3_exit
